# up phase: every second CU group of each XCD starts s_sleep 80 later so the two groups' epilogue store bursts do not coincide
# speedup vs baseline: 1.2637x; 1.0048x over previous
; __device__ __forceinline__ void build_rstd_table(LAS unsigned char* lds, const float* ssp, const pg8::StaticOrder& S, int tid) {
;     ...
;     for (int k = 0; k < 6; ++k) { pg8::Unit u; ok[k] = S.next((tid >> 8) + 2 * k, u);
;         if (ok[k]) { const f32x4* q = (const f32x4*)(ssp + (size_t)(u.pm * 256 + (tid & 255)) * 16);
; #pragma unroll
;             for (int j = 0; j < 4; ++j) p[k][j] = q[j]; } }
.LBB0_419:
	s_bfe_u32 s100, s96, 0x10003
	s_cmp_eq_u32 s100, 1
	s_cbranch_scc0 .Lstag_1
	s_sleep 80
	s_branch .Lstag_done
